# retention: + scalar-base load addressing, row decay factors and output-image lane constants hoisted out of the chunk loop
# speedup vs baseline: 1.0184x; 1.0023x over previous
.LBB0_590:
	v_lshl_add_u64 v[12:13], s[82:83], 0, v[8:9]
	s_mov_b32 s4, 0x100000
	v_add_co_u32_e32 v70, vcc, s4, v12
	v_lshl_add_u64 v[10:11], s[82:83], 0, v[6:7]
	s_mov_b32 s5, 0x101000
	v_addc_co_u32_e32 v71, vcc, 0, v13, vcc
	global_load_dword v3, v[10:11], off
	v_add_co_u32_e32 v102, vcc, s5, v12
	v_lshl_add_u64 v[74:75], s[82:83], 0, v[4:5]
	s_nop 0
	v_addc_co_u32_e32 v103, vcc, 0, v13, vcc
	global_load_dwordx4 v[10:13], v[102:103], off offset:-4096
	global_load_dwordx4 v[14:17], v[70:71], off offset:512
	global_load_dwordx4 v[50:53], v[70:71], off offset:32
	global_load_dwordx4 v[54:57], v[70:71], off offset:544
	global_load_dwordx4 v[58:61], v[70:71], off offset:64
	global_load_dwordx4 v[62:65], v[70:71], off offset:576
	global_load_dwordx4 v[66:69], v[70:71], off offset:96
	s_nop 0
	global_load_dwordx4 v[70:73], v[70:71], off offset:608
	s_nop 0
	global_load_dword v107, v[74:75], off
	s_nop 0
	global_load_dwordx4 v[74:77], v[102:103], off
	global_load_dwordx4 v[78:81], v[102:103], off offset:512
	global_load_dwordx4 v[82:85], v[102:103], off offset:32
	global_load_dwordx4 v[86:89], v[102:103], off offset:544
	global_load_dwordx4 v[90:93], v[102:103], off offset:64
	global_load_dwordx4 v[94:97], v[102:103], off offset:576
	global_load_dwordx4 v[98:101], v[102:103], off offset:96
	s_nop 0
	global_load_dwordx4 v[102:105], v[102:103], off offset:608
	s_add_i32 s11, s7, 1
	v_cvt_f32_u32_e32 v106, s7
	v_cvt_f32_u32_e32 v108, s11
	s_mov_b64 s[4:5], 0x2000
	v_lshl_add_u64 v[8:9], v[8:9], 0, s[4:5]
	v_mul_f32_e32 v109, v224, v106
	v_mul_f32_e32 v110, v224, v108
	v_cmp_gt_f32_e32 vcc, s0, v109
	v_cmp_gt_f32_e64 s[4:5], s0, v110
	v_lshl_add_u64 v[4:5], v[4:5], 0, s[94:95]
	v_cndmask_b32_e32 v109, 0, v220, vcc
	v_cndmask_b32_e64 v110, 0, v220, s[4:5]
	v_fmac_f32_e32 v109, v224, v106
	v_fmac_f32_e32 v110, v224, v108
	v_exp_f32_e32 v106, v109
	v_exp_f32_e32 v108, v110
	s_and_b64 s[4:5], s[4:5], exec
	s_cselect_b32 s11, 0xffffffc0, 0
	s_and_b64 s[4:5], vcc, exec
	s_cselect_b32 s4, 0xffffffc0, 0
	v_ldexp_f32 v109, v106, s4
	v_ldexp_f32 v106, v108, s11
	s_add_i32 s7, s7, -2
	v_lshl_add_u64 v[6:7], v[6:7], 0, s[94:95]
	s_cmp_eq_u32 s7, -2
	s_waitcnt vmcnt(0)
	v_mul_f32_e32 v106, v3, v106
	v_pk_fma_f32 v[10:11], v[106:107], v[10:11], v[18:19] op_sel_hi:[0,1,1]
	v_pk_fma_f32 v[14:15], v[106:107], v[14:15], v[34:35] op_sel_hi:[0,1,1]
	v_pk_fma_f32 v[12:13], v[106:107], v[12:13], v[20:21] op_sel_hi:[0,1,1]
	v_pk_fma_f32 v[16:17], v[106:107], v[16:17], v[36:37] op_sel_hi:[0,1,1]
	v_pk_fma_f32 v[22:23], v[106:107], v[50:51], v[22:23] op_sel_hi:[0,1,1]
	v_pk_fma_f32 v[38:39], v[106:107], v[54:55], v[38:39] op_sel_hi:[0,1,1]
	v_pk_fma_f32 v[24:25], v[106:107], v[52:53], v[24:25] op_sel_hi:[0,1,1]
	v_pk_fma_f32 v[40:41], v[106:107], v[56:57], v[40:41] op_sel_hi:[0,1,1]
	v_pk_fma_f32 v[26:27], v[106:107], v[58:59], v[26:27] op_sel_hi:[0,1,1]
	v_pk_fma_f32 v[42:43], v[106:107], v[62:63], v[42:43] op_sel_hi:[0,1,1]
	v_pk_fma_f32 v[28:29], v[106:107], v[60:61], v[28:29] op_sel_hi:[0,1,1]
	v_pk_fma_f32 v[44:45], v[106:107], v[64:65], v[44:45] op_sel_hi:[0,1,1]
	v_pk_fma_f32 v[30:31], v[106:107], v[66:67], v[30:31] op_sel_hi:[0,1,1]
	v_pk_fma_f32 v[46:47], v[106:107], v[70:71], v[46:47] op_sel_hi:[0,1,1]
	v_pk_fma_f32 v[32:33], v[106:107], v[68:69], v[32:33] op_sel_hi:[0,1,1]
	v_pk_fma_f32 v[48:49], v[106:107], v[72:73], v[48:49] op_sel_hi:[0,1,1]
	v_mul_f32_e32 v50, v107, v109
	v_pk_fma_f32 v[18:19], v[50:51], v[74:75], v[10:11] op_sel_hi:[0,1,1]
	v_pk_fma_f32 v[34:35], v[50:51], v[78:79], v[14:15] op_sel_hi:[0,1,1]
	v_pk_fma_f32 v[20:21], v[50:51], v[76:77], v[12:13] op_sel_hi:[0,1,1]
	v_pk_fma_f32 v[36:37], v[50:51], v[80:81], v[16:17] op_sel_hi:[0,1,1]
	v_pk_fma_f32 v[22:23], v[50:51], v[82:83], v[22:23] op_sel_hi:[0,1,1]
	v_pk_fma_f32 v[38:39], v[50:51], v[86:87], v[38:39] op_sel_hi:[0,1,1]
	v_pk_fma_f32 v[24:25], v[50:51], v[84:85], v[24:25] op_sel_hi:[0,1,1]
	v_pk_fma_f32 v[40:41], v[50:51], v[88:89], v[40:41] op_sel_hi:[0,1,1]
	v_pk_fma_f32 v[26:27], v[50:51], v[90:91], v[26:27] op_sel_hi:[0,1,1]
	v_pk_fma_f32 v[42:43], v[50:51], v[94:95], v[42:43] op_sel_hi:[0,1,1]
	v_pk_fma_f32 v[28:29], v[50:51], v[92:93], v[28:29] op_sel_hi:[0,1,1]
	v_pk_fma_f32 v[44:45], v[50:51], v[96:97], v[44:45] op_sel_hi:[0,1,1]
	v_pk_fma_f32 v[30:31], v[50:51], v[98:99], v[30:31] op_sel_hi:[0,1,1]
	v_pk_fma_f32 v[46:47], v[50:51], v[102:103], v[46:47] op_sel_hi:[0,1,1]
	v_pk_fma_f32 v[32:33], v[50:51], v[100:101], v[32:33] op_sel_hi:[0,1,1]
	v_pk_fma_f32 v[48:49], v[50:51], v[104:105], v[48:49] op_sel_hi:[0,1,1]
	s_cbranch_scc0 .LBB0_590
	s_ashr_i32 s52, s84, 5
	s_ashr_i32 s53, s52, 31
	s_lshl_b64 s[4:5], s[52:53], 12
	v_mov_b32_e32 v5, s5
	v_or_b32_e32 v4, s4, v154
	v_mov_b32_e32 v9, s5
	v_or_b32_e32 v8, s4, v156
	v_readlane_b32 s4, v255, 15
	v_lshlrev_b64 v[4:5], 11, v[4:5]
	v_readlane_b32 s5, v255, 16
	v_lshl_add_u64 v[6:7], s[86:87], 0, v[4:5]
	s_mov_b32 s7, s91
	v_lshl_add_u64 v[4:5], s[4:5], 0, v[4:5]
	v_lshlrev_b64 v[8:9], 12, v[8:9]
	v_lshl_add_u64 v[4:5], v[4:5], 0, s[6:7]
	v_mov_b32_e32 v169, v2
	s_and_b32 s11, s84, 7
	v_lshl_add_u64 v[16:17], v[4:5], 0, v[168:169]
	v_lshl_add_u64 v[4:5], s[88:89], 0, v[8:9]
	s_mov_b32 s55, s91
	v_lshl_add_u64 v[4:5], v[4:5], 0, s[54:55]
	s_lshl_b32 s4, s11, 7
	s_mov_b32 s5, s91
	v_lshl_add_u64 v[56:57], v[4:5], 0, s[4:5]
	s_mov_b32 s4, 0x10000
	v_lshl_add_u64 v[6:7], v[6:7], 0, s[6:7]
	v_add_co_u32_e32 v8, vcc, s4, v16
	v_lshl_add_u64 v[54:55], v[6:7], 0, v[168:169]
	s_nop 0
	v_addc_co_u32_e32 v9, vcc, 0, v17, vcc
	v_add_co_u32_e32 v58, vcc, s4, v54
	s_mov_b32 s4, 0x20000
	s_nop 0
	v_addc_co_u32_e32 v59, vcc, 0, v55, vcc
	v_add_co_u32_e32 v12, vcc, s4, v16
	global_load_dwordx4 v[114:117], v[16:17], off
	global_load_dwordx4 v[4:7], v[54:55], off
	v_addc_co_u32_e32 v13, vcc, 0, v17, vcc
	v_add_co_u32_e32 v60, vcc, s4, v54
	s_mov_b32 s4, 0x30000
	s_nop 0
	v_addc_co_u32_e32 v61, vcc, 0, v55, vcc
	v_add_co_u32_e32 v16, vcc, s4, v16
	v_mov_b32_e32 v171, v2
	s_nop 0
	v_addc_co_u32_e32 v17, vcc, 0, v17, vcc
	v_add_co_u32_e32 v62, vcc, s4, v54
	global_load_dwordx4 v[118:121], v[8:9], off
	s_nop 0
	global_load_dwordx4 v[8:11], v[58:59], off
	global_load_dwordx4 v[134:137], v[12:13], off
	s_nop 0
	global_load_dwordx4 v[12:15], v[60:61], off
	v_addc_co_u32_e32 v63, vcc, 0, v55, vcc
	global_load_dwordx4 v[142:145], v[16:17], off
	global_load_dwordx4 v[50:53], v[62:63], off
	v_lshl_add_u64 v[16:17], v[56:57], 0, v[170:171]
	s_mov_b32 s4, 0x40000
	v_add_co_u32_e32 v56, vcc, s4, v16
	s_lshl_b32 s4, s90, 6
	s_nop 0
	v_addc_co_u32_e32 v57, vcc, 0, v17, vcc
	global_load_dwordx4 v[122:125], v[16:17], off
	global_load_dwordx4 v[126:129], v[56:57], off
	s_add_i32 s4, s4, 0
	s_add_i32 s4, s4, 0x15800
	v_or_b32_e32 v16, s38, v1
	v_mov_b32_e32 v17, s4
	s_movk_i32 s4, 0x210
	v_mad_u32_u24 v16, v16, s4, v17
	v_add_u32_e32 v169, v16, v157
	v_cvt_pk_bf16_f32 v16, v18, v19
	v_cvt_pk_bf16_f32 v17, v20, v21
	v_cvt_pk_bf16_f32 v56, v22, v23
	v_cvt_pk_bf16_f32 v57, v24, v25
	ds_write2_b64 v169, v[16:17], v[56:57] offset1:2
	v_cvt_pk_bf16_f32 v16, v26, v27
	v_cvt_pk_bf16_f32 v17, v28, v29
	v_cvt_pk_bf16_f32 v56, v30, v31
	v_cvt_pk_bf16_f32 v57, v32, v33
	ds_write2_b64 v169, v[16:17], v[56:57] offset0:4 offset1:6
	v_cvt_pk_bf16_f32 v16, v34, v35
	v_cvt_pk_bf16_f32 v17, v36, v37
	v_cvt_pk_bf16_f32 v56, v38, v39
	v_cvt_pk_bf16_f32 v57, v40, v41
	ds_write2_b64 v169, v[16:17], v[56:57] offset0:32 offset1:34
	v_mul_f32_e32 v56, v224, v159
	v_cmp_gt_f32_e32 vcc, s0, v56
	v_cvt_pk_bf16_f32 v16, v42, v43
	v_cvt_pk_bf16_f32 v17, v44, v45
	v_cndmask_b32_e32 v56, 0, v220, vcc
	v_fmac_f32_e32 v56, v224, v159
	v_exp_f32_e32 v65, v56
	v_cvt_pk_bf16_f32 v56, v46, v47
	v_cvt_pk_bf16_f32 v57, v48, v49
	ds_write2_b64 v169, v[16:17], v[56:57] offset0:36 offset1:38
	v_mul_f32_e32 v16, v224, v194
	v_mul_f32_e32 v3, 0x43000000, v224
	v_cndmask_b32_e32 v64, 0, v222, vcc
	v_cmp_gt_f32_e32 vcc, s0, v16
	s_lshl_b32 s62, s9, 9
	s_waitcnt vmcnt(0)
	ds_write_b128 v223, v[4:7] offset:34816
	ds_write_b128 v223, v[8:11] offset:43520
	ds_write_b128 v223, v[12:15] offset:52224
	ds_write_b128 v223, v[50:53] offset:60928
	global_load_dwordx4 v[130:133], v[54:55], off offset:256
	global_load_dwordx4 v[138:141], v[58:59], off offset:256
	global_load_dwordx4 v[146:149], v[60:61], off offset:256
	global_load_dwordx4 v[150:153], v[62:63], off offset:256
	v_cndmask_b32_e32 v16, 0, v222, vcc
	v_cndmask_b32_e32 v17, 0, v220, vcc
	v_cmp_gt_f32_e32 vcc, s0, v3
	s_lshl_b32 s55, s10, 7
	s_lshl_b32 s58, s9, 6
	v_cndmask_b32_e32 v3, 0, v220, vcc
	v_fmac_f32_e32 v3, 0x43000000, v224
	v_exp_f32_e32 v3, v3
	s_lshl_b32 s59, s10, 3
	s_lshl_b32 s66, s90, 5
	s_and_b64 s[4:5], vcc, exec
	s_cselect_b32 s4, 0xffffffc0, 0
	v_ldexp_f32 v176, v3, s4
	s_lshl_b32 s4, s8, 2
	s_lshr_b32 s5, 0x31002210, s4
	s_lshr_b32 s4, 0x33323210, s4
	s_cmpk_lt_u32 s57, 0x80
	s_cselect_b64 s[80:81], -1, 0
	s_cmpk_gt_u32 s57, 0x7f
	s_cselect_b64 s[72:73], -1, 0
	s_lshl_b32 s4, s4, 5
	s_lshl_b32 s5, s5, 5
	s_and_b32 s39, s4, 0x60
	s_lshl_b32 s4, s8, 4
	s_lshl_b32 s6, s8, 5
	s_and_b32 s5, s5, 0x60
	s_and_b32 s4, s4, 0x3fffffe0
	s_and_b32 s6, s6, 32
	s_cmpk_gt_u32 s57, 0xff
	s_cselect_b64 s[78:79], -1, 0
	s_cmpk_gt_u32 s57, 0x17f
	s_cselect_b64 s[76:77], -1, 0
	s_lshl_b64 s[60:61], s[52:53], 23
	v_fmac_f32_e32 v17, v224, v194
	s_or_b32 s60, s60, s62
	s_lshl_b64 s[68:69], s[52:53], 24
	v_exp_f32_e32 v17, v17
	s_add_u32 s62, s55, s54
	v_and_b32_e32 v8, 4, v156
	s_addc_u32 s63, 0, 0
	s_lshl_b32 s57, s56, 2
	v_or_b32_e32 v8, s5, v8
	s_or_b32 s57, s57, s59
	v_or_b32_e32 v4, s39, v1
	v_or_b32_e32 v7, s4, v201
	v_or_b32_e32 v9, 2, v8
	v_or_b32_e32 v10, 3, v8
	v_or_b32_e32 v11, 8, v8
	v_add_u32_e32 v57, s39, v199
	s_lshl_b64 s[64:65], s[90:91], 13
	s_or_b32 s57, s57, s58
	v_ldexp_f32 v174, v17, v16
	v_or_b32_e32 v3, s5, v1
	v_or_b32_e32 v5, s4, v1
	v_or_b32_e32 v6, s6, v1
	v_lshl_add_u32 v225, v7, 1, v196
	v_or_b32_e32 v7, s6, v201
	v_lshlrev_b32_e32 v227, 1, v8
	v_cmp_gt_u32_e64 s[4:5], v8, v4
	v_cmp_lt_u32_e64 s[6:7], v8, v4
	v_cmp_gt_u32_e64 s[8:9], v9, v4
	v_cmp_gt_u32_e64 s[10:11], v10, v4
	v_cmp_gt_u32_e64 s[12:13], v11, v4
	v_or_b32_e32 v12, 9, v8
	v_or_b32_e32 v13, 10, v8
	v_or_b32_e32 v14, 11, v8
	v_or_b32_e32 v15, 16, v8
	v_or_b32_e32 v16, 17, v8
	v_or_b32_e32 v17, 18, v8
	v_or_b32_e32 v50, 19, v8
	v_or_b32_e32 v51, 24, v8
	v_or_b32_e32 v52, 25, v8
	v_or_b32_e32 v53, 26, v8
	v_or_b32_e32 v54, 27, v8
	v_or_b32_e32 v56, s38, v201
	v_cmp_gt_u32_e64 s[38:39], v8, v57
	v_cmp_lt_u32_e64 s[40:41], v8, v57
	v_cmp_gt_u32_e64 s[42:43], v9, v57
	v_cmp_gt_u32_e64 s[44:45], v10, v57
	v_cmp_gt_u32_e64 s[46:47], v11, v57
	s_or_b64 s[62:63], s[62:63], s[68:69]
	s_lshl_b64 s[52:53], s[52:53], 20
	s_or_b32 s57, s64, s57
	v_or_b32_e32 v8, s66, v155
	v_or_b32_e32 v9, s66, v252
	v_or_b32_e32 v10, s66, v253
	v_or_b32_e32 v11, s66, v254
	s_add_u32 s64, s57, s52
	v_cvt_f32_u32_e32 v8, v8
	v_cvt_f32_u32_e32 v9, v9
	v_cvt_f32_u32_e32 v10, v10
	v_cvt_f32_u32_e32 v11, v11
	s_addc_u32 s65, s65, s53
	s_lshl_b32 s56, s56, 6
	s_lshl_b64 s[58:59], s[90:91], 17
	s_or_b32 s55, s56, s55
	v_cmp_gt_u32_e64 s[14:15], v12, v4
	v_cmp_gt_u32_e64 s[16:17], v13, v4
	v_cmp_gt_u32_e64 s[18:19], v14, v4
	v_cmp_gt_u32_e64 s[20:21], v15, v4
	v_cmp_gt_u32_e64 s[48:49], v12, v57
	v_cmp_gt_u32_e64 s[50:51], v13, v57
	v_cmp_gt_u32_e64 s[52:53], v14, v57
	s_add_u32 s56, s55, s54
	v_cmp_gt_u32_e64 s[54:55], v15, v57
	v_or_b32_e32 v12, s66, v198
	v_or_b32_e32 v13, s66, v206
	v_or_b32_e32 v14, s66, v207
	v_or_b32_e32 v15, s66, v208
	s_addc_u32 s57, 0, 0
	v_add_f32_e32 v228, 0xc2fe0000, v8
	v_add_f32_e32 v229, 0xc2fe0000, v9
	v_add_f32_e32 v230, 0xc2fe0000, v10
	v_add_f32_e32 v231, 0xc2fe0000, v11
	v_cvt_f32_u32_e32 v8, v12
	v_cvt_f32_u32_e32 v9, v13
	v_cvt_f32_u32_e32 v10, v14
	v_cvt_f32_u32_e32 v11, v15
	s_or_b64 s[56:57], s[56:57], s[58:59]
	s_add_u32 s68, s56, s68
	v_cmp_gt_u32_e64 s[22:23], v16, v4
	v_cmp_gt_u32_e64 s[24:25], v17, v4
	v_cmp_gt_u32_e64 s[26:27], v50, v4
	s_addc_u32 s69, s57, s69
	v_cmp_gt_u32_e64 s[56:57], v16, v57
	v_cmp_gt_u32_e64 s[58:59], v17, v57
	v_lshl_add_u64 v[178:179], s[60:61], 0, v[162:163]
	v_cmp_gt_u32_e64 s[60:61], v50, v57
	v_or_b32_e32 v16, s66, v209
	v_or_b32_e32 v17, s66, v210
	v_or_b32_e32 v50, s66, v211
	v_or_b32_e32 v59, s66, v212
	v_add_f32_e32 v232, 0xc2fe0000, v8
	v_add_f32_e32 v233, 0xc2fe0000, v9
	v_add_f32_e32 v234, 0xc2fe0000, v10
	v_add_f32_e32 v235, 0xc2fe0000, v11
	v_cvt_f32_u32_e32 v8, v16
	v_cvt_f32_u32_e32 v9, v17
	v_cvt_f32_u32_e32 v10, v50
	v_cvt_f32_u32_e32 v11, v59
	v_or_b32_e32 v60, s66, v213
	v_or_b32_e32 v61, s66, v214
	v_or_b32_e32 v62, s66, v215
	v_or_b32_e32 v63, s66, v216
	v_add_f32_e32 v236, 0xc2fe0000, v8
	v_add_f32_e32 v237, 0xc2fe0000, v9
	v_add_f32_e32 v238, 0xc2fe0000, v10
	v_add_f32_e32 v239, 0xc2fe0000, v11
	v_cvt_f32_u32_e32 v8, v60
	v_cvt_f32_u32_e32 v9, v61
	v_cvt_f32_u32_e32 v10, v62
	v_cvt_f32_u32_e32 v11, v63
	v_or_b32_e32 v55, s66, v1
	v_ldexp_f32 v172, v65, v64
	v_mul_u32_u24_e32 v3, 0x110, v3
	v_mad_u32_u24 v171, v4, s93, 0
	v_mul_lo_u32 v5, v5, s93
	v_mul_u32_u24_e32 v6, 0x210, v6
	v_lshlrev_b32_e32 v7, 1, v7
	v_cmp_gt_u32_e64 s[28:29], v51, v4
	v_cmp_gt_u32_e64 s[30:31], v52, v4
	v_cmp_gt_u32_e64 s[34:35], v53, v4
	v_cmp_gt_u32_e64 s[36:37], v54, v4
	v_add_u32_e32 v4, 0, v227
	v_mul_lo_u32 v55, v55, s93
	v_lshlrev_b32_e32 v56, 1, v56
	v_mul_u32_u24_e32 v58, 0x110, v57
	s_mov_b32 s85, 32
	v_add_u32_e32 v226, 0x8800, v225
	v_lshl_add_u64 v[180:181], s[62:63], 0, v[164:165]
	v_cmp_gt_u32_e64 s[62:63], v51, v57
	v_lshl_add_u64 v[182:183], s[64:65], 0, v[160:161]
	v_cmp_gt_u32_e64 s[64:65], v52, v57
	v_lshl_add_u64 v[184:185], s[68:69], 0, v[166:167]
	v_cmp_gt_u32_e64 s[66:67], v53, v57
	v_mov_b32_e32 v173, v172
	v_mov_b32_e32 v186, v172
	v_mov_b32_e32 v187, v172
	v_mov_b32_e32 v175, v174
	v_mov_b32_e32 v188, v174
	v_mov_b32_e32 v189, v174
	v_add_f32_e32 v240, 0xc2fe0000, v8
	v_add_f32_e32 v241, 0xc2fe0000, v9
	v_add_f32_e32 v242, 0xc2fe0000, v10
	v_add_f32_e32 v243, 0xc2fe0000, v11
	v_mov_b32_e32 v190, v176
	v_mov_b32_e32 v191, v176
	v_add_u32_e32 v244, v4, v58
	v_add_u32_e32 v245, v195, v3
	v_add_u32_e32 v246, v195, v5
	v_add_u32_e32 v247, v217, v6
	v_add_u32_e32 v248, v197, v7
	v_add_u32_e32 v249, v195, v55
	v_add_u32_e32 v250, v200, v56
	v_cmp_gt_u32_e64 s[68:69], v54, v57
	v_lshrrev_b32_e32 v155, 6, v0
	v_lshrrev_b32_e32 v156, 8, v0
	v_add_u32_e32 v155, v155, v156
	v_mov_b32_e32 v156, 0x1dc00
	v_lshl_add_u32 v155, v155, 11, v156
	v_and_b32_e32 v156, 31, v0
	v_lshl_add_u32 v154, v156, 1, v155
	v_and_b32_e32 v157, 32, v0
	v_lshl_add_u32 v154, v157, 3, v154
	v_and_b32_e32 v160, 63, v0
	v_lshl_add_u32 v155, v160, 4, v155
	v_lshrrev_b32_e32 v161, 2, v160
	v_lshlrev_b32_e32 v161, 12, v161
	v_and_b32_e32 v162, 3, v0
	v_lshl_add_u32 v161, v162, 4, v161
	v_lshlrev_b32_e32 v156, 1, v156
	v_lshl_add_u32 v156, v157, 9, v156
	v_sub_u32_e32 v156, v161, v156
	v_add_u32_e32 v156, 0xfa00000, v156
	v_mul_f32_e32 v198, v228, v224
	v_mul_f32_e32 v199, v229, v224
	v_mul_f32_e32 v200, v230, v224
	v_mul_f32_e32 v201, v231, v224
	v_mul_f32_e32 v206, v232, v224
	v_mul_f32_e32 v207, v233, v224
	v_mul_f32_e32 v208, v234, v224
	v_mul_f32_e32 v209, v235, v224
	v_mul_f32_e32 v210, v236, v224
	v_mul_f32_e32 v211, v237, v224
	v_mul_f32_e32 v212, v238, v224
	v_mul_f32_e32 v213, v239, v224
	v_mul_f32_e32 v214, v240, v224
	v_mul_f32_e32 v215, v241, v224
	v_mul_f32_e32 v216, v242, v224
	v_mul_f32_e32 v217, v243, v224
	v_exp_f32_e32 v198, v198
	v_exp_f32_e32 v199, v199
	v_exp_f32_e32 v200, v200
	v_exp_f32_e32 v201, v201
	v_exp_f32_e32 v206, v206
	v_exp_f32_e32 v207, v207
	v_exp_f32_e32 v208, v208
	v_exp_f32_e32 v209, v209
	v_exp_f32_e32 v210, v210
	v_exp_f32_e32 v211, v211
	v_exp_f32_e32 v212, v212
	v_exp_f32_e32 v213, v213
	v_exp_f32_e32 v214, v214
	v_exp_f32_e32 v215, v215
	v_exp_f32_e32 v216, v216
	v_exp_f32_e32 v217, v217
	s_branch .LBB0_593

.LBB0_593:
	v_add_u32_e32 v4, 0x7a00000, v178
	v_add_u32_e32 v6, 0x7a10000, v178
	ds_write_b128 v223, v[114:117]
	ds_write_b128 v223, v[118:121] offset:8704
	ds_write_b128 v223, v[134:137] offset:17408
	ds_write_b128 v223, v[142:145] offset:26112
	global_load_dwordx4 v[114:117], v4, s[82:83] offset:256
	global_load_dwordx4 v[118:121], v6, s[82:83] offset:256
	v_add_u32_e32 v4, 0x7a20000, v178
	v_add_u32_e32 v6, 0x7a30000, v178
	v_lshlrev_b32_e32 v8, 16, v124
	v_and_b32_e32 v9, 0xffff0000, v124
	global_load_dwordx4 v[134:137], v4, s[82:83] offset:256
	global_load_dwordx4 v[142:145], v6, s[82:83] offset:256
	v_lshlrev_b32_e32 v4, 16, v122
	v_and_b32_e32 v5, 0xffff0000, v122
	v_lshlrev_b32_e32 v6, 16, v123
	v_and_b32_e32 v7, 0xffff0000, v123
	v_lshlrev_b32_e32 v10, 16, v125
	v_and_b32_e32 v11, 0xffff0000, v125
	v_pk_mul_f32 v[6:7], v[186:187], v[6:7]
	v_pk_mul_f32 v[4:5], v[172:173], v[4:5]
	v_pk_mul_f32 v[10:11], v[186:187], v[10:11]
	v_pk_mul_f32 v[8:9], v[172:173], v[8:9]
	v_cvt_pk_bf16_f32 v4, v4, v5
	v_cvt_pk_bf16_f32 v5, v6, v7
	v_cvt_pk_bf16_f32 v6, v8, v9
	v_cvt_pk_bf16_f32 v7, v10, v11
	ds_write_b128 v219, v[4:7]
	v_lshlrev_b32_e32 v4, 16, v126
	v_and_b32_e32 v5, 0xffff0000, v126
	v_lshlrev_b32_e32 v6, 16, v127
	v_and_b32_e32 v7, 0xffff0000, v127
	v_lshlrev_b32_e32 v8, 16, v128
	v_and_b32_e32 v9, 0xffff0000, v128
	v_lshlrev_b32_e32 v10, 16, v129
	v_and_b32_e32 v11, 0xffff0000, v129
	v_pk_mul_f32 v[6:7], v[188:189], v[6:7]
	v_pk_mul_f32 v[4:5], v[174:175], v[4:5]
	v_pk_mul_f32 v[10:11], v[188:189], v[10:11]
	v_pk_mul_f32 v[8:9], v[174:175], v[8:9]
	v_cvt_pk_bf16_f32 v4, v4, v5
	v_cvt_pk_bf16_f32 v5, v6, v7
	v_cvt_pk_bf16_f32 v6, v8, v9
	v_cvt_pk_bf16_f32 v7, v10, v11
	ds_write_b128 v219, v[4:7] offset:9216
	s_waitcnt lgkmcnt(0)
	s_barrier
	v_add_u32_e32 v251, v171, v158
	ds_read_b128 v[4:7], v245 offset:34816
	ds_read_b128 v[8:11], v251
	v_cndmask_b32_e64 v3, 0, 1, s[72:73]
	v_cmp_ne_u32_e64 s[70:71], 1, v3
	s_andn2_b64 vcc, exec, s[72:73]
	s_mov_b64 s[74:75], -1
	s_cbranch_vccnz .LBB0_595
	s_waitcnt lgkmcnt(0)
	v_mfma_f32_32x32x16_bf16 v[82:97], v[4:7], v[8:11], 0
	ds_read_b128 v[12:15], v245 offset:34848
	ds_read_b128 v[50:53], v251 offset:32
	s_mov_b64 s[74:75], 0
	s_waitcnt lgkmcnt(0)
	v_mfma_f32_32x32x16_bf16 v[82:97], v[12:15], v[50:53], v[82:97]
	ds_read_b128 v[12:15], v245 offset:34880
	ds_read_b128 v[50:53], v251 offset:64
	s_waitcnt lgkmcnt(0)
	v_mfma_f32_32x32x16_bf16 v[82:97], v[12:15], v[50:53], v[82:97]
	ds_read_b128 v[12:15], v245 offset:34912
	ds_read_b128 v[50:53], v251 offset:96
	s_waitcnt lgkmcnt(0)
	v_mfma_f32_32x32x16_bf16 v[82:97], v[12:15], v[50:53], v[82:97]
	ds_read_b128 v[12:15], v245 offset:34944
	ds_read_b128 v[50:53], v251 offset:128
	s_waitcnt lgkmcnt(0)
	v_mfma_f32_32x32x16_bf16 v[82:97], v[12:15], v[50:53], v[82:97]
	ds_read_b128 v[12:15], v245 offset:34976
	ds_read_b128 v[50:53], v251 offset:160
	s_waitcnt lgkmcnt(0)
	v_mfma_f32_32x32x16_bf16 v[82:97], v[12:15], v[50:53], v[82:97]
	ds_read_b128 v[12:15], v245 offset:35008
	ds_read_b128 v[50:53], v251 offset:192
	s_waitcnt lgkmcnt(0)
	v_mfma_f32_32x32x16_bf16 v[82:97], v[12:15], v[50:53], v[82:97]
	ds_read_b128 v[12:15], v245 offset:35040
	ds_read_b128 v[50:53], v251 offset:224
	s_waitcnt lgkmcnt(0)
	v_mfma_f32_32x32x16_bf16 v[82:97], v[12:15], v[50:53], v[82:97]

.LBB0_598:
	ds_read_b128 v[4:7], v246
	ds_read_b128 v[8:11], v247
	ds_read_b128 v[12:15], v246 offset:32
	ds_read_b128 v[98:101], v247 offset:32
	v_mov_b32_e32 v177, v176
	v_pk_mul_f32 v[18:19], v[190:191], v[18:19]
	s_waitcnt lgkmcnt(2)
	v_mfma_f32_32x32x16_bf16 v[50:65], v[4:7], v[8:11], 0
	v_mul_f32_e64 v32, v176, v32
	v_mul_f32_e64 v33, v177, v33
	v_mul_f32_e64 v30, v176, v30
	v_mul_f32_e64 v31, v177, v31
	v_mul_f32_e64 v28, v176, v28
	v_mul_f32_e64 v29, v177, v29
	v_pk_mul_f32 v[26:27], v[176:177], v[26:27]
	v_pk_mul_f32 v[24:25], v[176:177], v[24:25]
	v_pk_mul_f32 v[22:23], v[176:177], v[22:23]
	v_pk_mul_f32 v[20:21], v[176:177], v[20:21]
	s_waitcnt lgkmcnt(0)
	v_mfma_f32_32x32x16_bf16 v[50:65], v[12:15], v[98:101], v[50:65]
	ds_read_b128 v[4:7], v246 offset:64
	ds_read_b128 v[8:11], v247 offset:64
	ds_read_b128 v[12:15], v246 offset:96
	ds_read_b128 v[98:101], v247 offset:96
	s_cmp_lg_u32 s85, 1
	s_cselect_b64 s[74:75], -1, 0
	s_cmp_eq_u32 s85, 1
	s_waitcnt lgkmcnt(2)
	v_mfma_f32_32x32x16_bf16 v[50:65], v[4:7], v[8:11], v[50:65]
	s_waitcnt lgkmcnt(0)
	v_mfma_f32_32x32x16_bf16 v[50:65], v[12:15], v[98:101], v[50:65]
	ds_read_b128 v[4:7], v246 offset:128
	ds_read_b128 v[8:11], v247 offset:128
	ds_read_b128 v[12:15], v246 offset:160
	ds_read_b128 v[98:101], v247 offset:160
	s_waitcnt lgkmcnt(2)
	v_mfma_f32_32x32x16_bf16 v[50:65], v[4:7], v[8:11], v[50:65]
	ds_read_b64_tr_b16 v[4:5], v225 offset:34816
	ds_read_b64_tr_b16 v[6:7], v225 offset:35088
	ds_read_b64_tr_b16 v[8:9], v225 offset:39168
	ds_read_b64_tr_b16 v[10:11], v225 offset:39440
	ds_read_b64_tr_b16 v[102:103], v248
	ds_read_b64_tr_b16 v[104:105], v248 offset:144
	ds_read_b64_tr_b16 v[106:107], v248 offset:2304
	ds_read_b64_tr_b16 v[108:109], v248 offset:2448
	s_waitcnt lgkmcnt(2)
	v_mfma_f32_32x32x16_bf16 v[18:33], v[4:7], v[102:105], v[18:33]
	s_waitcnt lgkmcnt(0)
	v_mfma_f32_32x32x16_bf16 v[18:33], v[8:11], v[106:109], v[18:33]
	v_mfma_f32_32x32x16_bf16 v[50:65], v[12:15], v[98:101], v[50:65]
	ds_read_b64_tr_b16 v[4:5], v225 offset:43520
	ds_read_b64_tr_b16 v[6:7], v225 offset:43792
	ds_read_b64_tr_b16 v[8:9], v248 offset:4608
	ds_read_b64_tr_b16 v[10:11], v248 offset:4752
	ds_read_b64_tr_b16 v[12:13], v225 offset:47872
	ds_read_b64_tr_b16 v[14:15], v225 offset:48144
	ds_read_b64_tr_b16 v[98:99], v248 offset:6912
	ds_read_b64_tr_b16 v[100:101], v248 offset:7056
	s_waitcnt lgkmcnt(4)
	v_mfma_f32_32x32x16_bf16 v[18:33], v[4:7], v[8:11], v[18:33]
	s_waitcnt lgkmcnt(0)
	v_mfma_f32_32x32x16_bf16 v[18:33], v[12:15], v[98:101], v[18:33]
	ds_read_b64_tr_b16 v[4:5], v225 offset:52224
	ds_read_b64_tr_b16 v[6:7], v225 offset:52496
	ds_read_b64_tr_b16 v[8:9], v248 offset:9216
	ds_read_b64_tr_b16 v[10:11], v248 offset:9360
	ds_read_b64_tr_b16 v[12:13], v225 offset:56576
	ds_read_b64_tr_b16 v[14:15], v225 offset:56848
	ds_read_b64_tr_b16 v[98:99], v248 offset:11520
	ds_read_b64_tr_b16 v[100:101], v248 offset:11664
	s_waitcnt lgkmcnt(4)
	v_mfma_f32_32x32x16_bf16 v[18:33], v[4:7], v[8:11], v[18:33]
	ds_read_b128 v[4:7], v246 offset:192
	ds_read_b128 v[8:11], v246 offset:224
	ds_read_b128 v[102:105], v247 offset:192
	ds_read_b128 v[106:109], v247 offset:224
	s_waitcnt lgkmcnt(4)
	v_mfma_f32_32x32x16_bf16 v[18:33], v[12:15], v[98:101], v[18:33]
	ds_read_b64_tr_b16 v[12:13], v225 offset:60928
	ds_read_b64_tr_b16 v[14:15], v225 offset:61200
	ds_read_b64_tr_b16 v[98:99], v225 offset:65280
	ds_read_b64_tr_b16 v[100:101], v226 offset:30736
	ds_read_b64_tr_b16 v[110:111], v248 offset:13824
	ds_read_b64_tr_b16 v[112:113], v248 offset:13968
	ds_read_b64_tr_b16 v[202:203], v248 offset:16128
	ds_read_b64_tr_b16 v[204:205], v248 offset:16272
	s_waitcnt lgkmcnt(0)
	s_barrier
	s_waitcnt vmcnt(3)
	ds_write_b128 v223, v[114:117]
	ds_write_b128 v223, v[130:133] offset:34816
	s_waitcnt vmcnt(2)
	ds_write_b128 v223, v[118:121] offset:8704
	ds_write_b128 v223, v[138:141] offset:43520
	s_waitcnt vmcnt(1)
	ds_write_b128 v223, v[134:137] offset:17408
	ds_write_b128 v223, v[146:149] offset:52224
	s_waitcnt vmcnt(0)
	ds_write_b128 v223, v[142:145] offset:26112
	ds_write_b128 v223, v[150:153] offset:60928
	v_mfma_f32_32x32x16_bf16 v[18:33], v[12:15], v[110:113], v[18:33]
	v_mfma_f32_32x32x16_bf16 v[50:65], v[4:7], v[102:105], v[50:65]
	v_mfma_f32_32x32x16_bf16 v[18:33], v[98:101], v[202:205], v[18:33]
	v_mfma_f32_32x32x16_bf16 v[50:65], v[8:11], v[106:109], v[50:65]
	s_nop 10
	v_cvt_pk_bf16_f32 v12, v18, v19
	v_cvt_pk_bf16_f32 v13, v20, v21
	v_cvt_pk_bf16_f32 v14, v22, v23
	v_cvt_pk_bf16_f32 v15, v24, v25
	v_cvt_pk_bf16_f32 v4, v26, v27
	v_cvt_pk_bf16_f32 v5, v28, v29
	v_cvt_pk_bf16_f32 v6, v30, v31
	v_cvt_pk_bf16_f32 v7, v32, v33
	ds_write2_b64 v169, v[12:13], v[14:15] offset1:2
	ds_write2_b64 v169, v[4:5], v[6:7] offset0:4 offset1:6
	s_cbranch_scc1 .LBB0_600
	v_add_u32_e32 v4, 0x7a40000, v178
	v_add_u32_e32 v6, 0xba40000, v178
	global_load_dwordx4 v[114:117], v4, s[82:83]
	global_load_dwordx4 v[130:133], v6, s[82:83]
	v_add_u32_e32 v4, 0x7a50000, v178
	v_add_u32_e32 v6, 0xba50000, v178
	global_load_dwordx4 v[118:121], v4, s[82:83]
	global_load_dwordx4 v[138:141], v6, s[82:83]
	v_add_u32_e32 v4, 0x7a60000, v178
	v_add_u32_e32 v6, 0xba60000, v178
	global_load_dwordx4 v[134:137], v4, s[82:83]
	global_load_dwordx4 v[146:149], v6, s[82:83]
	v_add_u32_e32 v4, 0x7a70000, v178
	v_add_u32_e32 v6, 0xba70000, v178
	global_load_dwordx4 v[142:145], v4, s[82:83]
	global_load_dwordx4 v[150:153], v6, s[82:83]
	v_add_u32_e32 v6, 0xfa80000, v180
	v_add_u32_e32 v4, 0xfac0000, v180
	global_load_dwordx4 v[122:125], v6, s[82:83]
	global_load_dwordx4 v[126:129], v4, s[82:83]

.LBB0_610:
	v_mov_b32_e32 v3, v224
	s_and_b64 vcc, exec, s[74:75]
	s_waitcnt vmcnt(0)
	s_cbranch_vccz .LBB0_612
	v_add_u32_e32 v4, 0xba40000, v178
	ds_write_b128 v223, v[130:133] offset:34816
	ds_write_b128 v223, v[138:141] offset:43520
	ds_write_b128 v223, v[146:149] offset:52224
	ds_write_b128 v223, v[150:153] offset:60928
	v_add_u32_e32 v6, 0xba50000, v178
	global_load_dwordx4 v[130:133], v4, s[82:83] offset:256
	global_load_dwordx4 v[138:141], v6, s[82:83] offset:256
	v_add_u32_e32 v4, 0xba60000, v178
	v_add_u32_e32 v6, 0xba70000, v178
	global_load_dwordx4 v[146:149], v4, s[82:83] offset:256
	global_load_dwordx4 v[150:153], v6, s[82:83] offset:256
.LBB0_612:
	v_lshl_add_u64 v[4:5], s[82:83], 0, v[184:185]
	v_mul_f32_e32 v8, v176, v198
	v_mul_f32_e32 v8, v50, v8
	s_nop 4
	v_fmac_f32_e32 v8, v66, v198
	v_bfe_u32 v7, v8, 16, 1
	v_add3_u32 v9, v8, v7, s1
	ds_write_b16_d16_hi v154, v9
	v_mul_f32_e32 v6, v176, v199
	v_mul_f32_e32 v11, v51, v6
	v_mul_f32_e32 v13, v176, v200
	v_fmac_f32_e32 v11, v67, v199
	v_mul_f32_e32 v13, v52, v13
	v_bfe_u32 v6, v11, 16, 1
	v_fmac_f32_e32 v13, v68, v200
	v_add3_u32 v10, v11, v6, s1
	v_bfe_u32 v12, v13, 16, 1
	s_nop 0
	v_add3_u32 v12, v13, v12, s1
	ds_write_b16_d16_hi v154, v10 offset:64
	ds_write_b16_d16_hi v154, v12 offset:128
	v_mul_f32_e32 v6, v176, v201
	v_mul_f32_e32 v15, v53, v6
	v_fmac_f32_e32 v15, v69, v201
	v_bfe_u32 v6, v15, 16, 1
	v_add3_u32 v14, v15, v6, s1
	s_nop 0
	ds_write_b16_d16_hi v154, v14 offset:192
	v_mul_f32_e32 v6, v176, v206
	v_mul_f32_e32 v17, v54, v6
	v_fmac_f32_e32 v17, v70, v206
	v_bfe_u32 v6, v17, 16, 1
	v_add3_u32 v16, v17, v6, s1
	v_mul_f32_e32 v51, v176, v207
	v_mul_f32_e32 v51, v55, v51
	v_fmac_f32_e32 v51, v71, v207
	v_bfe_u32 v50, v51, 16, 1
	v_add3_u32 v50, v51, v50, s1
	ds_write_b16_d16_hi v154, v16 offset:512
	ds_write_b16_d16_hi v154, v50 offset:576
	v_mul_f32_e32 v6, v176, v208
	v_mul_f32_e32 v53, v56, v6
	v_fmac_f32_e32 v53, v72, v208
	v_bfe_u32 v6, v53, 16, 1
	v_add3_u32 v52, v53, v6, s1
	v_mul_f32_e32 v55, v176, v209
	v_mul_f32_e32 v55, v57, v55
	v_fmac_f32_e32 v55, v73, v209
	v_bfe_u32 v54, v55, 16, 1
	s_nop 0
	v_add3_u32 v54, v55, v54, s1
	ds_write_b16_d16_hi v154, v52 offset:640
	ds_write_b16_d16_hi v154, v54 offset:704
	v_mul_f32_e32 v6, v176, v210
	v_mul_f32_e32 v57, v58, v6
	v_fmac_f32_e32 v57, v74, v210
	v_bfe_u32 v6, v57, 16, 1
	v_add3_u32 v56, v57, v6, s1
	s_nop 0
	v_mul_f32_e32 v66, v176, v211
	v_mul_f32_e32 v59, v59, v66
	v_fmac_f32_e32 v59, v75, v211
	v_bfe_u32 v58, v59, 16, 1
	v_add3_u32 v58, v59, v58, s1
	ds_write_b16_d16_hi v154, v56 offset:1024
	ds_write_b16_d16_hi v154, v58 offset:1088
	v_mul_f32_e32 v6, v176, v212
	v_mul_f32_e32 v60, v60, v6
	v_fmac_f32_e32 v60, v76, v212
	v_bfe_u32 v6, v60, 16, 1
	v_add3_u32 v66, v60, v6, s1
	s_nop 0
	v_mul_f32_e32 v68, v176, v213
	v_mul_f32_e32 v61, v61, v68
	v_fmac_f32_e32 v61, v77, v213
	v_bfe_u32 v67, v61, 16, 1
	v_add3_u32 v67, v61, v67, s1
	ds_write_b16_d16_hi v154, v66 offset:1152
	ds_write_b16_d16_hi v154, v67 offset:1216
	v_mul_f32_e32 v6, v176, v214
	v_mul_f32_e32 v62, v62, v6
	v_fmac_f32_e32 v62, v78, v214
	v_bfe_u32 v6, v62, 16, 1
	v_add3_u32 v68, v62, v6, s1
	s_nop 0
	v_mul_f32_e32 v70, v176, v215
	v_mul_f32_e32 v63, v63, v70
	v_fmac_f32_e32 v63, v79, v215
	v_bfe_u32 v69, v63, 16, 1
	v_add3_u32 v69, v63, v69, s1
	ds_write_b16_d16_hi v154, v68 offset:1536
	ds_write_b16_d16_hi v154, v69 offset:1600
	v_mul_f32_e32 v7, v176, v216
	v_mul_f32_e32 v69, v176, v217
	v_mul_f32_e32 v7, v64, v7
	v_mul_f32_e32 v65, v65, v69
	v_fmac_f32_e32 v7, v80, v216
	v_fmac_f32_e32 v65, v81, v217
	v_bfe_u32 v64, v7, 16, 1
	v_bfe_u32 v3, v65, 16, 1
	v_mul_f32_e32 v9, v8, v8
	v_mul_f32_e32 v10, v11, v11
	v_add3_u32 v64, v7, v64, s1
	v_add3_u32 v3, v65, v3, s1
	v_mul_f32_e32 v12, v13, v13
	v_mul_f32_e32 v14, v15, v15
	v_mul_f32_e32 v16, v17, v17
	v_mul_f32_e32 v50, v51, v51
	ds_write_b16_d16_hi v154, v64 offset:1664
	ds_write_b16_d16_hi v154, v3 offset:1728
	v_add_co_u32_e32 v194, vcc, v4, v156
	s_nop 1
	v_addc_co_u32_e32 v195, vcc, 0, v5, vcc
	v_add_co_u32_e32 v196, vcc, 0x10000, v194
	s_nop 1
	v_addc_co_u32_e32 v197, vcc, 0, v195, vcc
	v_mov_b32_dpp v4, v9 row_shr:1 row_mask:0xf bank_mask:0xf bound_ctrl:1
	v_mov_b32_dpp v5, v10 row_shr:1 row_mask:0xf bank_mask:0xf bound_ctrl:1
	v_mul_f32_e32 v52, v53, v53
	v_mul_f32_e32 v54, v55, v55
	v_mul_f32_e32 v56, v57, v57
	v_mul_f32_e32 v58, v59, v59
	v_mul_f32_e32 v66, v60, v60
	v_mul_f32_e32 v67, v61, v61
	v_mul_f32_e32 v68, v62, v62
	v_mul_f32_e32 v6, v63, v63
	v_mul_f32_e32 v64, v7, v7
	v_mul_f32_e32 v3, v65, v65
	v_fmac_f32_e32 v4, v8, v8
	v_fmac_f32_e32 v5, v11, v11
	v_mov_b32_dpp v8, v12 row_shr:1 row_mask:0xf bank_mask:0xf bound_ctrl:1
	v_mov_b32_dpp v9, v14 row_shr:1 row_mask:0xf bank_mask:0xf bound_ctrl:1
	v_mov_b32_dpp v10, v16 row_shr:1 row_mask:0xf bank_mask:0xf bound_ctrl:1
	v_mov_b32_dpp v11, v50 row_shr:1 row_mask:0xf bank_mask:0xf bound_ctrl:1
	v_fmac_f32_e32 v8, v13, v13
	v_fmac_f32_e32 v9, v15, v15
	v_fmac_f32_e32 v10, v17, v17
	v_fmac_f32_e32 v11, v51, v51
	v_mov_b32_dpp v12, v52 row_shr:1 row_mask:0xf bank_mask:0xf bound_ctrl:1
	v_mov_b32_dpp v13, v54 row_shr:1 row_mask:0xf bank_mask:0xf bound_ctrl:1
	v_mov_b32_dpp v14, v56 row_shr:1 row_mask:0xf bank_mask:0xf bound_ctrl:1
	v_mov_b32_dpp v15, v58 row_shr:1 row_mask:0xf bank_mask:0xf bound_ctrl:1
	v_mov_b32_dpp v16, v66 row_shr:1 row_mask:0xf bank_mask:0xf bound_ctrl:1
	v_mov_b32_dpp v17, v67 row_shr:1 row_mask:0xf bank_mask:0xf bound_ctrl:1
	v_mov_b32_dpp v50, v68 row_shr:1 row_mask:0xf bank_mask:0xf bound_ctrl:1
	v_mov_b32_dpp v6, v6 row_shr:1 row_mask:0xf bank_mask:0xf bound_ctrl:1
	v_mov_b32_dpp v51, v64 row_shr:1 row_mask:0xf bank_mask:0xf bound_ctrl:1
	v_mov_b32_dpp v3, v3 row_shr:1 row_mask:0xf bank_mask:0xf bound_ctrl:1
	v_fmac_f32_e32 v12, v53, v53
	v_fmac_f32_e32 v13, v55, v55
	v_fmac_f32_e32 v14, v57, v57
	v_fmac_f32_e32 v15, v59, v59
	v_fmac_f32_e32 v16, v60, v60
	v_fmac_f32_e32 v17, v61, v61
	v_fmac_f32_e32 v50, v62, v62
	v_fmac_f32_e32 v6, v63, v63
	v_fmac_f32_e32 v51, v7, v7
	v_fmac_f32_e32 v3, v65, v65
	s_waitcnt lgkmcnt(0)
	ds_read_b128 v[160:163], v155
	ds_read_b128 v[164:167], v155 offset:1024
	v_add_f32_dpp v4, v4, v4 row_shr:2 row_mask:0xf bank_mask:0xf bound_ctrl:1
	v_add_f32_dpp v5, v5, v5 row_shr:2 row_mask:0xf bank_mask:0xf bound_ctrl:1
	v_add_f32_dpp v7, v8, v8 row_shr:2 row_mask:0xf bank_mask:0xf bound_ctrl:1
	v_add_f32_dpp v8, v9, v9 row_shr:2 row_mask:0xf bank_mask:0xf bound_ctrl:1
	v_add_f32_dpp v9, v10, v10 row_shr:2 row_mask:0xf bank_mask:0xf bound_ctrl:1
	v_add_f32_dpp v10, v11, v11 row_shr:2 row_mask:0xf bank_mask:0xf bound_ctrl:1
	v_add_f32_dpp v11, v12, v12 row_shr:2 row_mask:0xf bank_mask:0xf bound_ctrl:1
	v_add_f32_dpp v12, v13, v13 row_shr:2 row_mask:0xf bank_mask:0xf bound_ctrl:1
	v_add_f32_dpp v13, v14, v14 row_shr:2 row_mask:0xf bank_mask:0xf bound_ctrl:1
	v_add_f32_dpp v14, v15, v15 row_shr:2 row_mask:0xf bank_mask:0xf bound_ctrl:1
	v_add_f32_dpp v15, v16, v16 row_shr:2 row_mask:0xf bank_mask:0xf bound_ctrl:1
	v_add_f32_dpp v16, v17, v17 row_shr:2 row_mask:0xf bank_mask:0xf bound_ctrl:1
	v_add_f32_dpp v17, v50, v50 row_shr:2 row_mask:0xf bank_mask:0xf bound_ctrl:1
	v_add_f32_dpp v6, v6, v6 row_shr:2 row_mask:0xf bank_mask:0xf bound_ctrl:1
	v_add_f32_dpp v50, v51, v51 row_shr:2 row_mask:0xf bank_mask:0xf bound_ctrl:1
	v_add_f32_dpp v3, v3, v3 row_shr:2 row_mask:0xf bank_mask:0xf bound_ctrl:1
	v_add_f32_dpp v4, v4, v4 row_shr:4 row_mask:0xf bank_mask:0xf bound_ctrl:1
	v_add_f32_dpp v5, v5, v5 row_shr:4 row_mask:0xf bank_mask:0xf bound_ctrl:1
	v_add_f32_dpp v7, v7, v7 row_shr:4 row_mask:0xf bank_mask:0xf bound_ctrl:1
	v_add_f32_dpp v8, v8, v8 row_shr:4 row_mask:0xf bank_mask:0xf bound_ctrl:1
	v_add_f32_dpp v9, v9, v9 row_shr:4 row_mask:0xf bank_mask:0xf bound_ctrl:1
	v_add_f32_dpp v10, v10, v10 row_shr:4 row_mask:0xf bank_mask:0xf bound_ctrl:1
	v_add_f32_dpp v11, v11, v11 row_shr:4 row_mask:0xf bank_mask:0xf bound_ctrl:1
	v_add_f32_dpp v12, v12, v12 row_shr:4 row_mask:0xf bank_mask:0xf bound_ctrl:1
	v_add_f32_dpp v13, v13, v13 row_shr:4 row_mask:0xf bank_mask:0xf bound_ctrl:1
	v_add_f32_dpp v14, v14, v14 row_shr:4 row_mask:0xf bank_mask:0xf bound_ctrl:1
	v_add_f32_dpp v15, v15, v15 row_shr:4 row_mask:0xf bank_mask:0xf bound_ctrl:1
	v_add_f32_dpp v16, v16, v16 row_shr:4 row_mask:0xf bank_mask:0xf bound_ctrl:1
	v_add_f32_dpp v17, v17, v17 row_shr:4 row_mask:0xf bank_mask:0xf bound_ctrl:1
	v_add_f32_dpp v51, v6, v6 row_shr:4 row_mask:0xf bank_mask:0xf bound_ctrl:1
	v_add_f32_dpp v53, v50, v50 row_shr:4 row_mask:0xf bank_mask:0xf bound_ctrl:1
	v_add_f32_dpp v54, v3, v3 row_shr:4 row_mask:0xf bank_mask:0xf bound_ctrl:1
	v_add_f32_dpp v3, v4, v4 row_shr:8 row_mask:0xf bank_mask:0xf bound_ctrl:1
	v_add_f32_dpp v4, v5, v5 row_shr:8 row_mask:0xf bank_mask:0xf bound_ctrl:1
	v_add_f32_dpp v5, v7, v7 row_shr:8 row_mask:0xf bank_mask:0xf bound_ctrl:1
	v_add_f32_dpp v6, v8, v8 row_shr:8 row_mask:0xf bank_mask:0xf bound_ctrl:1
	v_add_f32_dpp v7, v9, v9 row_shr:8 row_mask:0xf bank_mask:0xf bound_ctrl:1
	v_add_f32_dpp v8, v10, v10 row_shr:8 row_mask:0xf bank_mask:0xf bound_ctrl:1
	v_add_f32_dpp v9, v11, v11 row_shr:8 row_mask:0xf bank_mask:0xf bound_ctrl:1
	v_add_f32_dpp v10, v12, v12 row_shr:8 row_mask:0xf bank_mask:0xf bound_ctrl:1
	v_add_f32_dpp v11, v13, v13 row_shr:8 row_mask:0xf bank_mask:0xf bound_ctrl:1
	v_add_f32_dpp v13, v14, v14 row_shr:8 row_mask:0xf bank_mask:0xf bound_ctrl:1
	v_add_f32_dpp v15, v15, v15 row_shr:8 row_mask:0xf bank_mask:0xf bound_ctrl:1
	v_add_f32_dpp v16, v16, v16 row_shr:8 row_mask:0xf bank_mask:0xf bound_ctrl:1
	v_add_f32_dpp v50, v17, v17 row_shr:8 row_mask:0xf bank_mask:0xf bound_ctrl:1
	v_add_f32_dpp v52, v51, v51 row_shr:8 row_mask:0xf bank_mask:0xf bound_ctrl:1
	v_add_f32_dpp v53, v53, v53 row_shr:8 row_mask:0xf bank_mask:0xf bound_ctrl:1
	v_add_f32_dpp v55, v54, v54 row_shr:8 row_mask:0xf bank_mask:0xf bound_ctrl:1
	s_waitcnt lgkmcnt(0)
	global_store_dwordx4 v[194:195], v[160:163], off
	global_store_dwordx4 v[196:197], v[164:167], off
	v_mov_b32_dpp v12, v3 quad_perm:[0, 1, 2, 3] row_mask:0xf bank_mask:0x8
	v_mov_b32_dpp v12, v4 row_shl:1 row_mask:0xf bank_mask:0x8
	v_mov_b32_dpp v12, v5 row_shl:2 row_mask:0xf bank_mask:0x8
	v_mov_b32_dpp v12, v6 row_shl:3 row_mask:0xf bank_mask:0x8
	v_mov_b32_dpp v12, v7 row_shl:4 row_mask:0xf bank_mask:0x4
	v_mov_b32_dpp v12, v8 row_shl:5 row_mask:0xf bank_mask:0x4
	v_mov_b32_dpp v12, v9 row_shl:6 row_mask:0xf bank_mask:0x4
	v_mov_b32_dpp v12, v10 row_shl:7 row_mask:0xf bank_mask:0x4
	v_mov_b32_dpp v12, v11 row_shl:8 row_mask:0xf bank_mask:0x2
	v_mov_b32_dpp v12, v13 row_shl:9 row_mask:0xf bank_mask:0x2
	v_mov_b32_dpp v12, v15 row_shl:10 row_mask:0xf bank_mask:0x2
	v_mov_b32_dpp v12, v16 row_shl:11 row_mask:0xf bank_mask:0x2
	v_mov_b32_dpp v12, v50 row_shl:12 row_mask:0xf bank_mask:0x1
	v_mov_b32_dpp v12, v52 row_shl:13 row_mask:0xf bank_mask:0x1
	v_mov_b32_dpp v12, v53 row_shl:14 row_mask:0xf bank_mask:0x1
	v_mov_b32_dpp v12, v55 row_shl:15 row_mask:0xf bank_mask:0x1
	v_mov_b32_e32 v14, v12
	v_and_b32_e32 v50, 15, v0
	v_xor_b32_e32 v50, 15, v50
	v_lshrrev_b32_e32 v51, 2, v50
	v_and_b32_e32 v50, 3, v50
	v_lshlrev_b32_e32 v51, 11, v51
	v_lshl_or_b32 v50, v50, 8, v51
	v_add_u32_e32 v50, 0x200000, v50
	v_lshl_add_u64 v[4:5], s[82:83], 0, v[182:183]
	v_permlane16_swap_b32_e32 v12, v14
	v_add_co_u32_e32 v4, vcc, v4, v50
	v_add_f32_e32 v12, v12, v14
	s_nop 0
	v_addc_co_u32_e32 v5, vcc, 0, v5, vcc
	s_mov_b64 s[70:71], exec
	s_mov_b32 exec_lo, 0xffff
	s_mov_b32 exec_hi, 0xffff
	global_store_dword v[4:5], v12, off
	s_branch .LBB0_592
